# scan L2 prefetch of next chunk's C/B tiles moved earlier, to l-tile 3 of the y pass
# speedup vs baseline: 1.0084x; 1.0021x over previous
; #define LAS __attribute__((address_space(3)))
; template <int MODE> __device__ __forceinline__ void ssd_scan_phase(Frame& F, int j, bool ctx_out) {
;     ...
;                     const int l = 16 * lt + fr; const float cl = tab[l];
;                     f32x4 accd[2], acco[2];
;                     accd[0] = accd[1] = acco[0] = acco[1] = (f32x4){0.f, 0.f, 0.f, 0.f};
;                     const int kd = lt >> 1;
;                     if ((lt & 1) == 0) { xb_cur = xb_nxt; if (kd + 1 < 4) xb_nxt = *(const bf16x8*)(xl + (size_t)16 * T + 32 * (kd + 1)); }
;                     const bf16x8 xa = xf[0][kd], xb = xb_cur;
; #pragma unroll
;                     for (int ks = 0; ks < 4; ++ks) {
;                         const bool full = dir == 0 ? (ks < kd) : (ks > kd);
;                         if (full) {
;                             const bf16x8 gf = *(const LAS bf16x8*)(GS + l * 256 + (((4 * ks + fq) ^ fr) << 4));
;                             const float f1 = __builtin_amdgcn_exp2f(cl - tab[dir == 0 ? 32 * ks + 31 : 32 * ks]);
;                             const f32x4 z4 = (f32x4){0.f, 0.f, 0.f, 0.f};
;                             const f32x4 t0 = __builtin_amdgcn_mfma_f32_16x16x32_bf16(xs2[0][ks], gf, z4, 0, 0, 0), t1 = __builtin_amdgcn_mfma_f32_16x16x32_bf16(xs2[1][ks], gf, z4, 0, 0, 0);
;                             accd[0] += t0 * f1; accd[1] += t1 * f1;
;                         }
;                     }
; #pragma unroll
;                     for (int q = 0; q < 4; ++q) {
;                         const u32x2 lo = *(const LAS u32x2*)(CS + l * 256 + (((4 * q + (fq >> 1)) ^ fr) << 4) + (fq & 1) * 8), hi = *(const LAS u32x2*)(CS + l * 256 + (((4 * q + 2 + (fq >> 1)) ^ fr) << 4) + (fq & 1) * 8);
;                         u32x4 c4; c4.x = lo.x; c4.y = lo.y; c4.z = hi.x; c4.w = hi.y; const bf16x8 cfr = __builtin_bit_cast(bf16x8, c4);
;                         acco[0] = __builtin_amdgcn_mfma_f32_16x16x32_bf16(hf[0][q], cfr, acco[0], 0, 0, 0);
;                         acco[1] = __builtin_amdgcn_mfma_f32_16x16x32_bf16(hf[1][q], cfr, acco[1], 0, 0, 0);
;                     }
;     ...
;                 const int kn = k + 1; const bool isctxn = kn < 2; const int ccn = isctxn ? (dir == 0 ? kn : 1 - kn) : (dir == 0 ? kn - 2 : 17 - kn);
;                 const int row0n = isctxn ? MLAT + b * LCTX + ccn * 128 : b * LSEQ + ccn * 128;
.LBB0_506:
	v_mbcnt_lo_u32_b32 v179, -1, 0
	v_mbcnt_hi_u32_b32 v179, -1, v179
	s_sub_i32 s100, s4, 1
	s_sub_i32 s101, 16, s4
	s_cmp_lg_u32 s38, 0
	s_cselect_b32 s100, s100, s101
	v_and_b32_e32 v178, 3, v179
	s_lshl_b32 s100, s100, 7
	s_add_i32 s100, s100, s81
	s_cmp_eq_u32 s4, 0
	s_cselect_b32 s100, s76, s100
	s_cmp_eq_u32 s4, 17
	s_cselect_b32 s100, s81, s100
	v_lshl_add_u32 v178, v178, 5, v188
	v_and_b32_e32 v179, 4, v179
	s_lshl_b32 s100, s100, 11
	v_lshlrev_b32_e32 v178, 11, v178
	v_lshl_add_u32 v178, v179, 5, v178
	s_mov_b32 m0, 0x1c000
	v_add_u32_e32 v178, s100, v178
	s_mov_b32 s100, s77
	s_mov_b32 s101, s73
	global_load_lds_dword v178, s[100:101]
	global_load_lds_dword v178, s[74:75]
	v_add3_u32 v178, 0, v223, v195
	v_add_u32_e32 v179, v178, v185
	ds_read_b64 v[224:225], v179
	v_add_u32_e32 v179, v178, v183
	ds_read_b64 v[226:227], v179
	v_add_u32_e32 v179, v178, v187
	ds_read_b64 v[232:233], v179
	v_add_u32_e32 v179, v178, v213
	ds_read_b64 v[234:235], v179
	s_waitcnt lgkmcnt(2)
	v_mfma_f32_16x16x32_bf16 v[228:231], v[116:119], v[224:227], 0
	v_add_u32_e32 v179, v178, v212
	ds_read_b64 v[246:247], v179
	v_add_u32_e32 v179, v178, v211
	v_mfma_f32_16x16x32_bf16 v[224:227], v[124:127], v[224:227], 0
	ds_read_b64 v[248:249], v179
	v_add_u32_e32 v174, v174, v172
	v_sub_f32_e32 v168, v175, v168
	s_waitcnt lgkmcnt(2)
	v_mfma_f32_16x16x32_bf16 v[228:231], v[112:115], v[232:235], v[228:231]
	v_exp_f32_e32 v168, v168
	v_add_u32_e32 v179, v178, v191
	v_add_u32_e32 v178, v178, v210
	v_mfma_f32_16x16x32_bf16 v[224:227], v[120:123], v[232:235], v[224:227]
	ds_read_b64 v[232:233], v179
	ds_read_b64 v[234:235], v178
	v_sub_f32_e32 v169, v175, v169
	s_waitcnt lgkmcnt(2)
	v_mfma_f32_16x16x32_bf16 v[228:231], v[108:111], v[246:249], v[228:231]
	v_exp_f32_e32 v169, v169
	v_sub_f32_e32 v170, v175, v170
	v_exp_f32_e32 v170, v170
	v_mfma_f32_16x16x32_bf16 v[224:227], v[128:131], v[246:249], v[224:227]
	ds_read_b128 v[246:249], v174
	v_add_u32_e32 v174, 32, v180
	s_waitcnt lgkmcnt(1)
	v_mfma_f32_16x16x32_bf16 v[228:231], v[104:107], v[232:235], v[228:231]
	v_cmp_le_i32_e32 vcc, v174, v173
	v_cmp_eq_u32_e64 s[100:101], v174, v173
	s_xnor_b64 vcc, vcc, s[38:39]
	s_andn2_b64 s[100:101], s[100:101], s[38:39]
	s_or_b64 vcc, vcc, s[100:101]
	s_waitcnt lgkmcnt(0)
; #define LAS __attribute__((address_space(3)))
; __device__ __forceinline__ unsigned cvt_pk_bf16(float lo, float hi) { const f32x2 v = {lo, hi}; return __builtin_bit_cast(unsigned, __builtin_convertvector(v, bf16x2_t)); }
; __device__ __forceinline__ u32x4 pack8(const float (&f)[8]) { u32x4 w; w.x = cvt_pk_bf16(f[0], f[1]); w.y = cvt_pk_bf16(f[2], f[3]); w.z = cvt_pk_bf16(f[4], f[5]); w.w = cvt_pk_bf16(f[6], f[7]); return w; }
; template <int MODE> __device__ __forceinline__ void ssd_scan_phase(Frame& F, int j, bool ctx_out) {
;     ...
;                     if ((lt & 1) == 0) { xb_cur = xb_nxt; if (kd + 1 < 4) xb_nxt = *(const bf16x8*)(xl + (size_t)16 * T + 32 * (kd + 1)); }
;     ...
;                         float gg[8]; unpack8(*(const LAS u32x4*)(GS + l * 256 + (((4 * kd + fq) ^ fr) << 4)), gg);
;                         const f32x4 ca = *(const LAS f32x4*)(tab + 32 * kd + 8 * fq), cb = *(const LAS f32x4*)(tab + 32 * kd + 8 * fq + 4);
;                         const f32x4 da = *(const LAS f32x4*)(tab + 128 + 32 * kd + 8 * fq), db = *(const LAS f32x4*)(tab + 128 + 32 * kd + 8 * fq + 4);
;                         const float cs[8] = {ca.x, ca.y, ca.z, ca.w, cb.x, cb.y, cb.z, cb.w}, ds[8] = {da.x, da.y, da.z, da.w, db.x, db.y, db.z, db.w};
;                         float m[8];
; #pragma unroll
;                         for (int jj = 0; jj < 8; ++jj) { const int s = 32 * kd + 8 * fq + jj; const bool valid = dir == 0 ? (s <= l) : (s >= l);
;                             const float e = valid ? __builtin_amdgcn_exp2f(cl - cs[jj]) : 0.f; m[jj] = gg[jj] * e * ds[jj]; if (dir == 0 && s == l) m[jj] += dsk; }
;                         const bf16x8 mf = __builtin_bit_cast(bf16x8, pack8(m));
;                         accd[0] = __builtin_amdgcn_mfma_f32_16x16x32_bf16(xa, mf, accd[0], 0, 0, 0);
;                         accd[1] = __builtin_amdgcn_mfma_f32_16x16x32_bf16(xb, mf, accd[1], 0, 0, 0);
;                     }
;                     const float el = __builtin_amdgcn_exp2f(cl);
; #pragma unroll
;                     for (int pt = 0; pt < 2; ++pt) { const f32x4 y = accd[pt] + acco[pt] * el; u32x2 o; o.x = cvt_pk_bf16(y[0], y[1]); o.y = cvt_pk_bf16(y[2], y[3]);
;                         *(u32x2*)(yout + (size_t)(row0 + l) * DI + h * 64 + ph * 32 + 16 * pt + 4 * fq) = o; }
;                 }
	v_lshlrev_b32_e32 v178, 16, v246
	v_cndmask_b32_e32 v168, 0, v168, vcc
	v_mul_f32_e32 v168, v168, v178
	v_cmp_eq_u32_e32 vcc, v174, v173
	v_mul_f32_e32 v178, v164, v168
	s_and_b64 vcc, s[38:39], vcc
	v_fma_f32 v164, v164, v168, v203
	v_cndmask_b32_e32 v164, v178, v164, vcc
	v_and_b32_e32 v179, 0xffff0000, v246
	v_cmp_le_i32_e32 vcc, v216, v173
	v_cmp_eq_u32_e64 s[100:101], v216, v173
	s_xnor_b64 vcc, vcc, s[38:39]
	s_andn2_b64 s[100:101], s[100:101], s[38:39]
	s_or_b64 vcc, vcc, s[100:101]
	v_lshlrev_b32_e32 v223, 16, v247
	v_cndmask_b32_e32 v168, 0, v169, vcc
	v_mul_f32_e32 v168, v168, v179
	v_cmp_eq_u32_e32 vcc, v216, v173
	v_mul_f32_e32 v169, v165, v168
	s_and_b64 vcc, s[38:39], vcc
	v_fma_f32 v165, v165, v168, v203
	v_cndmask_b32_e32 v165, v169, v165, vcc
	v_cmp_le_i32_e32 vcc, v217, v173
	v_cmp_eq_u32_e64 s[100:101], v217, v173
	s_xnor_b64 vcc, vcc, s[38:39]
	s_andn2_b64 s[100:101], s[100:101], s[38:39]
	s_or_b64 vcc, vcc, s[100:101]
	v_mfma_f32_16x16x32_bf16 v[224:227], v[132:135], v[232:235], v[224:227]
	v_and_b32_e32 v232, 0xffff0000, v247
	v_cndmask_b32_e32 v168, 0, v170, vcc
	v_mul_f32_e32 v168, v168, v223
	v_cmp_eq_u32_e32 vcc, v217, v173
	v_mul_f32_e32 v169, v166, v168
	s_and_b64 vcc, s[38:39], vcc
	v_fma_f32 v166, v166, v168, v203
	v_cndmask_b32_e32 v166, v169, v166, vcc
	v_sub_f32_e32 v170, v175, v171
	v_exp_f32_e32 v170, v170
	v_cmp_le_i32_e32 vcc, v218, v173
	v_cmp_eq_u32_e64 s[100:101], v218, v173
	s_xnor_b64 vcc, vcc, s[38:39]
	s_andn2_b64 s[100:101], s[100:101], s[38:39]
	s_or_b64 vcc, vcc, s[100:101]
	v_sub_f32_e32 v160, v175, v160
	v_cndmask_b32_e32 v168, 0, v170, vcc
	v_mul_f32_e32 v168, v168, v232
	v_cmp_eq_u32_e32 vcc, v218, v173
	v_mul_f32_e32 v169, v167, v168
	s_and_b64 vcc, s[38:39], vcc
	v_fma_f32 v167, v167, v168, v203
	v_cndmask_b32_e32 v167, v169, v167, vcc
	v_exp_f32_e32 v160, v160
	v_cmp_le_i32_e32 vcc, v219, v173
	v_cmp_eq_u32_e64 s[100:101], v219, v173
	s_xnor_b64 vcc, vcc, s[38:39]
	s_andn2_b64 s[100:101], s[100:101], s[38:39]
	s_or_b64 vcc, vcc, s[100:101]
	v_lshlrev_b32_e32 v233, 16, v248
	v_cndmask_b32_e32 v160, 0, v160, vcc
	v_mul_f32_e32 v160, v160, v233
	v_cmp_eq_u32_e32 vcc, v219, v173
	v_mul_f32_e32 v168, v156, v160
	s_and_b64 vcc, s[38:39], vcc
	v_fma_f32 v156, v156, v160, v203
	v_cndmask_b32_e32 v160, v168, v156, vcc
	v_sub_f32_e32 v161, v175, v161
	v_exp_f32_e32 v161, v161
	v_cmp_le_i32_e32 vcc, v220, v173
	v_cmp_eq_u32_e64 s[100:101], v220, v173
	s_xnor_b64 vcc, vcc, s[38:39]
	s_andn2_b64 s[100:101], s[100:101], s[38:39]
	s_or_b64 vcc, vcc, s[100:101]
	v_and_b32_e32 v234, 0xffff0000, v248
	v_cndmask_b32_e32 v156, 0, v161, vcc
	v_mul_f32_e32 v156, v156, v234
	v_cmp_eq_u32_e32 vcc, v220, v173
	v_mul_f32_e32 v161, v157, v156
	s_and_b64 vcc, s[38:39], vcc
	v_fma_f32 v156, v157, v156, v203
	v_cndmask_b32_e32 v161, v161, v156, vcc
	v_sub_f32_e32 v162, v175, v162
	v_exp_f32_e32 v162, v162
	v_cmp_le_i32_e32 vcc, v221, v173
	v_cmp_eq_u32_e64 s[100:101], v221, v173
	s_xnor_b64 vcc, vcc, s[38:39]
	s_andn2_b64 s[100:101], s[100:101], s[38:39]
	s_or_b64 vcc, vcc, s[100:101]
	v_lshlrev_b32_e32 v235, 16, v249
	v_cndmask_b32_e32 v156, 0, v162, vcc
	v_mul_f32_e32 v156, v156, v235
	v_cmp_eq_u32_e32 vcc, v221, v173
	v_mul_f32_e32 v157, v158, v156
	s_and_b64 vcc, s[38:39], vcc
	v_fma_f32 v156, v158, v156, v203
	v_cndmask_b32_e32 v162, v157, v156, vcc
	v_sub_f32_e32 v158, v175, v163
	v_exp_f32_e32 v158, v158
	v_cmp_le_i32_e32 vcc, v222, v173
	v_cmp_eq_u32_e64 s[100:101], v222, v173
	s_xnor_b64 vcc, vcc, s[38:39]
	s_andn2_b64 s[100:101], s[100:101], s[38:39]
	s_or_b64 vcc, vcc, s[100:101]
	v_and_b32_e32 v236, 0xffff0000, v249
	ds_read_b32 v170, v214 offset:256
	v_cndmask_b32_e32 v156, 0, v158, vcc
	v_mul_f32_e32 v156, v156, v236
	v_cmp_eq_u32_e32 vcc, v222, v173
	v_mul_f32_e32 v157, v159, v156
	s_and_b64 vcc, s[38:39], vcc
	v_fma_f32 v156, v159, v156, v203
	v_cndmask_b32_e32 v159, v157, v156, vcc
	v_cvt_pk_bf16_f32 v156, v164, v165
	v_cvt_pk_bf16_f32 v157, v166, v167
	v_cvt_pk_bf16_f32 v158, v160, v161
	v_cvt_pk_bf16_f32 v159, v162, v159
	s_mov_b32 s94, s92
	s_mov_b32 s95, s92
	v_mfma_f32_16x16x32_bf16 v[136:139], v[136:139], v[156:159], v[144:147]
	v_or_b32_e32 v169, 64, v176
	s_mov_b32 s93, s92
	s_and_b64 vcc, exec, s[46:47]
	v_mfma_f32_16x16x32_bf16 v[144:147], v[148:151], v[156:159], v[152:155]
	v_exp_f32_e32 v148, v175
	v_add_u32_e32 v150, s5, v173
	v_ashrrev_i32_e32 v151, 31, v150
	v_lshlrev_b64 v[150:151], 13, v[150:151]
	v_pk_fma_f32 v[138:139], v[148:149], v[230:231], v[138:139] op_sel_hi:[0,1,1]
	v_pk_fma_f32 v[136:137], v[148:149], v[228:229], v[136:137] op_sel_hi:[0,1,1]
	v_lshl_add_u64 v[150:151], v[198:199], 0, v[150:151]
	v_cvt_pk_bf16_f32 v136, v136, v137
	v_cvt_pk_bf16_f32 v137, v138, v139
	global_store_dwordx2 v[150:151], v[136:137], off
	v_pk_fma_f32 v[136:137], v[148:149], v[226:227], v[146:147] op_sel_hi:[0,1,1]
	v_pk_fma_f32 v[138:139], v[148:149], v[224:225], v[144:145] op_sel_hi:[0,1,1]
	v_cvt_pk_bf16_f32 v138, v138, v139
	v_cvt_pk_bf16_f32 v139, v136, v137
	global_store_dwordx2 v[150:151], v[138:139], off offset:32
	global_load_dwordx4 v[136:139], v[200:201], off offset:192
	v_mov_b64_e32 v[146:147], s[94:95]
	v_lshlrev_b32_e32 v152, 8, v169
	v_mov_b64_e32 v[150:151], s[94:95]
	v_mov_b64_e32 v[144:145], s[92:93]
	v_add_u32_e32 v156, s87, v152
	v_mov_b64_e32 v[148:149], s[92:93]
	s_cbranch_vccz .LBB0_532
	s_and_b64 vcc, exec, s[46:47]
	s_cbranch_vccz .LBB0_533

; #define LAS __attribute__((address_space(3)))
; template <int MODE> __device__ __forceinline__ void ssd_scan_phase(Frame& F, int j, bool ctx_out) {
;     ...
;                     const int l = 16 * lt + fr; const float cl = tab[l];
;                     f32x4 accd[2], acco[2];
;                     accd[0] = accd[1] = acco[0] = acco[1] = (f32x4){0.f, 0.f, 0.f, 0.f};
;                     const int kd = lt >> 1;
;                     if ((lt & 1) == 0) { xb_cur = xb_nxt; if (kd + 1 < 4) xb_nxt = *(const bf16x8*)(xl + (size_t)16 * T + 32 * (kd + 1)); }
;                     const bf16x8 xa = xf[0][kd], xb = xb_cur;
; #pragma unroll
;                     for (int ks = 0; ks < 4; ++ks) {
;                         const bool full = dir == 0 ? (ks < kd) : (ks > kd);
;                         if (full) {
;                             const bf16x8 gf = *(const LAS bf16x8*)(GS + l * 256 + (((4 * ks + fq) ^ fr) << 4));
;                             const float f1 = __builtin_amdgcn_exp2f(cl - tab[dir == 0 ? 32 * ks + 31 : 32 * ks]);
;                             const f32x4 z4 = (f32x4){0.f, 0.f, 0.f, 0.f};
;                             const f32x4 t0 = __builtin_amdgcn_mfma_f32_16x16x32_bf16(xs2[0][ks], gf, z4, 0, 0, 0), t1 = __builtin_amdgcn_mfma_f32_16x16x32_bf16(xs2[1][ks], gf, z4, 0, 0, 0);
;                             accd[0] += t0 * f1; accd[1] += t1 * f1;
;                         }
;                     }
; #pragma unroll
;                     for (int q = 0; q < 4; ++q) {
;                         const u32x2 lo = *(const LAS u32x2*)(CS + l * 256 + (((4 * q + (fq >> 1)) ^ fr) << 4) + (fq & 1) * 8), hi = *(const LAS u32x2*)(CS + l * 256 + (((4 * q + 2 + (fq >> 1)) ^ fr) << 4) + (fq & 1) * 8);
;                         u32x4 c4; c4.x = lo.x; c4.y = lo.y; c4.z = hi.x; c4.w = hi.y; const bf16x8 cfr = __builtin_bit_cast(bf16x8, c4);
;                         acco[0] = __builtin_amdgcn_mfma_f32_16x16x32_bf16(hf[0][q], cfr, acco[0], 0, 0, 0);
;                         acco[1] = __builtin_amdgcn_mfma_f32_16x16x32_bf16(hf[1][q], cfr, acco[1], 0, 0, 0);
;                     }
;                     {
;                         float gg[8]; unpack8(*(const LAS u32x4*)(GS + l * 256 + (((4 * kd + fq) ^ fr) << 4)), gg);
;                         const f32x4 ca = *(const LAS f32x4*)(tab + 32 * kd + 8 * fq), cb = *(const LAS f32x4*)(tab + 32 * kd + 8 * fq + 4);
.LBB0_510:
	v_add3_u32 v157, 0, v152, v195
	v_add_u32_e32 v152, v157, v185
	v_add_u32_e32 v153, v157, v183
	ds_read_b64 v[158:159], v152
	ds_read_b64 v[160:161], v153
	v_add_u32_e32 v152, v157, v187
	v_add_u32_e32 v154, v157, v213
	ds_read_b64 v[152:153], v152
	ds_read_b32 v171, v214 offset:320
	ds_read_b64 v[154:155], v154
	s_waitcnt lgkmcnt(3)
	v_mfma_f32_16x16x32_bf16 v[162:165], v[116:119], v[158:161], 0
	v_add_u32_e32 v166, v157, v212
	v_add_u32_e32 v167, v157, v211
	v_add_u32_e32 v168, v157, v191
	v_mfma_f32_16x16x32_bf16 v[158:161], v[124:127], v[158:161], 0
	ds_read_b64 v[216:217], v166
	ds_read_b64 v[218:219], v167
	ds_read_b64 v[220:221], v168
	v_add_u32_e32 v157, v157, v210
	ds_read_b64 v[222:223], v157
	s_waitcnt lgkmcnt(4)
	v_mfma_f32_16x16x32_bf16 v[162:165], v[112:115], v[152:155], v[162:165]
	v_lshlrev_b32_e32 v168, 4, v206
	v_add_u32_e32 v156, v156, v168
	s_mov_b32 s94, s92
	v_mfma_f32_16x16x32_bf16 v[152:155], v[120:123], v[152:155], v[158:161]
	s_mov_b32 s95, s92
	s_mov_b32 s93, s92
	s_waitcnt lgkmcnt(2)
	v_mfma_f32_16x16x32_bf16 v[158:161], v[108:111], v[216:219], v[162:165]
	s_nop 2
	ds_read_b128 v[164:167], v197 offset:256
	v_mfma_f32_16x16x32_bf16 v[152:155], v[128:131], v[216:219], v[152:155]
	ds_read_b128 v[216:219], v156
	s_waitcnt lgkmcnt(1)
	v_sub_f32_e32 v228, v170, v165
	v_mfma_f32_16x16x32_bf16 v[224:227], v[104:107], v[220:223], v[158:161]
	s_waitcnt lgkmcnt(0)
	v_lshlrev_b32_e32 v173, 16, v216
	v_and_b32_e32 v174, 0xffff0000, v216
	v_lshlrev_b32_e32 v175, 16, v217
	v_mfma_f32_16x16x32_bf16 v[220:223], v[132:135], v[220:223], v[152:155]
	ds_read_b128 v[156:159], v197 offset:272
	ds_read_b128 v[160:163], v197 offset:768
	v_and_b32_e32 v178, 0xffff0000, v217
	v_sub_f32_e32 v152, v170, v164
	v_exp_f32_e32 v200, v152
	v_lshlrev_b32_e32 v179, 16, v218
	v_and_b32_e32 v216, 0xffff0000, v218
	v_lshlrev_b32_e32 v217, 16, v219
	v_cndmask_b32_e64 v200, 0, v200, s[40:41]
	v_mul_f32_e32 v173, v200, v173
	s_waitcnt lgkmcnt(0)
	v_mul_f32_e32 v200, v160, v173
	v_fma_f32 v173, v160, v173, v203
	v_and_b32_e32 v218, 0xffff0000, v219
	v_cndmask_b32_e64 v219, v200, v173, s[42:43]
	v_add_u32_e32 v173, 0x41, v180
	v_exp_f32_e32 v228, v228
	v_sub_f32_e32 v229, v170, v166
	v_exp_f32_e32 v229, v229
	v_sub_f32_e32 v230, v170, v167
	v_cmp_le_i32_e32 vcc, v173, v169
	v_cmp_eq_u32_e64 s[100:101], v173, v169
	s_xnor_b64 vcc, vcc, s[38:39]
	s_andn2_b64 s[100:101], s[100:101], s[38:39]
	s_or_b64 vcc, vcc, s[100:101]
	v_exp_f32_e32 v230, v230
	v_sub_f32_e32 v231, v170, v156
	v_cndmask_b32_e32 v200, 0, v228, vcc
	v_mul_f32_e32 v174, v200, v174
	v_cmp_eq_u32_e32 vcc, v173, v169
	v_mul_f32_e32 v200, v161, v174
	v_fma_f32 v174, v161, v174, v203
	s_and_b64 vcc, s[38:39], vcc
	v_cndmask_b32_e32 v228, v200, v174, vcc
	v_add_u32_e32 v174, 0x42, v180
	v_exp_f32_e32 v231, v231
	ds_read_b128 v[152:155], v197 offset:784
	v_sub_f32_e32 v232, v170, v157
	v_exp_f32_e32 v232, v232
	v_cmp_le_i32_e32 vcc, v174, v169
	v_cmp_eq_u32_e64 s[100:101], v174, v169
	s_xnor_b64 vcc, vcc, s[38:39]
	s_andn2_b64 s[100:101], s[100:101], s[38:39]
	s_or_b64 vcc, vcc, s[100:101]
	v_sub_f32_e32 v233, v170, v158
	v_exp_f32_e32 v233, v233
	v_cndmask_b32_e32 v200, 0, v229, vcc
	v_mul_f32_e32 v175, v200, v175
	v_cmp_eq_u32_e32 vcc, v174, v169
	v_mul_f32_e32 v200, v162, v175
	v_fma_f32 v175, v162, v175, v203
	s_and_b64 vcc, s[38:39], vcc
	v_cndmask_b32_e32 v229, v200, v175, vcc
	v_add_u32_e32 v175, 0x43, v180
	v_sub_f32_e32 v234, v170, v159
	v_exp_f32_e32 v234, v234
	v_cvt_pk_bf16_f32 v228, v219, v228
	v_exp_f32_e32 v170, v170
	v_cmp_le_i32_e32 vcc, v175, v169
	v_cmp_eq_u32_e64 s[100:101], v175, v169
	s_xnor_b64 vcc, vcc, s[38:39]
	s_andn2_b64 s[100:101], s[100:101], s[38:39]
	s_or_b64 vcc, vcc, s[100:101]
	v_cndmask_b32_e32 v200, 0, v230, vcc
	v_mul_f32_e32 v178, v200, v178
	v_cmp_eq_u32_e32 vcc, v175, v169
	v_mul_f32_e32 v200, v163, v178
	v_fma_f32 v178, v163, v178, v203
	s_and_b64 vcc, s[38:39], vcc
	v_cndmask_b32_e32 v178, v200, v178, vcc
	v_add_u32_e32 v200, 0x44, v180
	v_cvt_pk_bf16_f32 v229, v229, v178
	s_nop 0
	s_nop 1
	v_cmp_le_i32_e32 vcc, v200, v169
	v_cmp_eq_u32_e64 s[100:101], v200, v169
	s_xnor_b64 vcc, vcc, s[38:39]
	s_andn2_b64 s[100:101], s[100:101], s[38:39]
	s_or_b64 vcc, vcc, s[100:101]
	v_cndmask_b32_e32 v201, 0, v231, vcc
	v_mul_f32_e32 v179, v201, v179
	v_cmp_eq_u32_e32 vcc, v200, v169
	s_waitcnt lgkmcnt(0)
; __device__ __forceinline__ unsigned cvt_pk_bf16(float lo, float hi) { const f32x2 v = {lo, hi}; return __builtin_bit_cast(unsigned, __builtin_convertvector(v, bf16x2_t)); }
; __device__ __forceinline__ u32x4 pack8(const float (&f)[8]) { u32x4 w; w.x = cvt_pk_bf16(f[0], f[1]); w.y = cvt_pk_bf16(f[2], f[3]); w.z = cvt_pk_bf16(f[4], f[5]); w.w = cvt_pk_bf16(f[6], f[7]); return w; }
; template <int MODE> __device__ __forceinline__ void ssd_scan_phase(Frame& F, int j, bool ctx_out) {
;     ...
;                         for (int jj = 0; jj < 8; ++jj) { const int s = 32 * kd + 8 * fq + jj; const bool valid = dir == 0 ? (s <= l) : (s >= l);
;                             const float e = valid ? __builtin_amdgcn_exp2f(cl - cs[jj]) : 0.f; m[jj] = gg[jj] * e * ds[jj]; if (dir == 0 && s == l) m[jj] += dsk; }
;                         const bf16x8 mf = __builtin_bit_cast(bf16x8, pack8(m));
;                         accd[0] = __builtin_amdgcn_mfma_f32_16x16x32_bf16(xa, mf, accd[0], 0, 0, 0);
;                         accd[1] = __builtin_amdgcn_mfma_f32_16x16x32_bf16(xb, mf, accd[1], 0, 0, 0);
;                     }
;                     const float el = __builtin_amdgcn_exp2f(cl);
; #pragma unroll
;                     for (int pt = 0; pt < 2; ++pt) { const f32x4 y = accd[pt] + acco[pt] * el; u32x2 o; o.x = cvt_pk_bf16(y[0], y[1]); o.y = cvt_pk_bf16(y[2], y[3]);
;                         *(u32x2*)(yout + (size_t)(row0 + l) * DI + h * 64 + ph * 32 + 16 * pt + 4 * fq) = o; }
;                 }
	v_mul_f32_e32 v201, v152, v179
	v_fma_f32 v179, v152, v179, v203
	s_and_b64 vcc, s[38:39], vcc
	v_cndmask_b32_e32 v179, v201, v179, vcc
	v_add_u32_e32 v201, 0x45, v180
	s_nop 1
	s_nop 1
	v_cmp_le_i32_e32 vcc, v201, v169
	v_cmp_eq_u32_e64 s[100:101], v201, v169
	s_xnor_b64 vcc, vcc, s[38:39]
	s_andn2_b64 s[100:101], s[100:101], s[38:39]
	s_or_b64 vcc, vcc, s[100:101]
	v_cndmask_b32_e32 v230, 0, v232, vcc
	v_mul_f32_e32 v216, v230, v216
	v_cmp_eq_u32_e32 vcc, v201, v169
	v_mul_f32_e32 v230, v153, v216
	v_fma_f32 v216, v153, v216, v203
	s_and_b64 vcc, s[38:39], vcc
	v_cndmask_b32_e32 v230, v230, v216, vcc
	v_add_u32_e32 v216, 0x46, v180
	v_cvt_pk_bf16_f32 v230, v179, v230
	s_nop 0
	s_nop 1
	v_cmp_le_i32_e32 vcc, v216, v169
	v_cmp_eq_u32_e64 s[100:101], v216, v169
	s_xnor_b64 vcc, vcc, s[38:39]
	s_andn2_b64 s[100:101], s[100:101], s[38:39]
	s_or_b64 vcc, vcc, s[100:101]
	v_cndmask_b32_e32 v231, 0, v233, vcc
	v_mul_f32_e32 v217, v231, v217
	v_cmp_eq_u32_e32 vcc, v216, v169
	v_mul_f32_e32 v231, v154, v217
	v_fma_f32 v217, v154, v217, v203
	s_and_b64 vcc, s[38:39], vcc
	v_cndmask_b32_e32 v231, v231, v217, vcc
	v_add_u32_e32 v217, 0x47, v180
	s_nop 1
	s_nop 1
	v_cmp_le_i32_e32 vcc, v217, v169
	v_cmp_eq_u32_e64 s[100:101], v217, v169
	s_xnor_b64 vcc, vcc, s[38:39]
	s_andn2_b64 s[100:101], s[100:101], s[38:39]
	s_or_b64 vcc, vcc, s[100:101]
	v_cndmask_b32_e32 v232, 0, v234, vcc
	v_mul_f32_e32 v218, v232, v218
	v_cmp_eq_u32_e32 vcc, v217, v169
	v_mul_f32_e32 v232, v155, v218
	v_fma_f32 v218, v155, v218, v203
	s_and_b64 vcc, s[38:39], vcc
	v_cndmask_b32_e32 v218, v232, v218, vcc
	v_cvt_pk_bf16_f32 v231, v231, v218
	v_add_u32_e32 v218, s5, v169
	v_ashrrev_i32_e32 v219, 31, v218
	v_mfma_f32_16x16x32_bf16 v[232:235], v[100:103], v[228:231], v[148:151]
	v_lshlrev_b64 v[218:219], 13, v[218:219]
	v_lshl_add_u64 v[218:219], v[198:199], 0, v[218:219]
	v_or_b32_e32 v169, 0x50, v176
	s_waitcnt vmcnt(7)
	v_mfma_f32_16x16x32_bf16 v[144:147], v[140:143], v[228:231], v[144:147]
	v_mov_b64_e32 v[150:151], s[94:95]
	s_nop 2
	v_pk_fma_f32 v[226:227], v[170:171], v[226:227], v[234:235] op_sel_hi:[0,1,1]
	v_pk_fma_f32 v[224:225], v[170:171], v[224:225], v[232:233] op_sel_hi:[0,1,1]
	v_cvt_pk_bf16_f32 v224, v224, v225
	v_cvt_pk_bf16_f32 v225, v226, v227
	v_pk_fma_f32 v[146:147], v[170:171], v[222:223], v[146:147] op_sel_hi:[0,1,1]
	v_pk_fma_f32 v[144:145], v[170:171], v[220:221], v[144:145] op_sel_hi:[0,1,1]
	v_cvt_pk_bf16_f32 v144, v144, v145
	v_cvt_pk_bf16_f32 v145, v146, v147
	global_store_dwordx2 v[218:219], v[224:225], off
	global_store_dwordx2 v[218:219], v[144:145], off offset:32
	v_lshlrev_b32_e32 v218, 8, v169
	v_mov_b64_e32 v[146:147], s[94:95]
	v_mov_b64_e32 v[148:149], s[92:93]
	v_add_u32_e32 v170, s87, v218
	s_and_b64 vcc, exec, s[46:47]
	v_mov_b64_e32 v[144:145], s[92:93]
	s_cbranch_vccz .LBB0_534
	s_and_b64 vcc, exec, s[46:47]
	s_cbranch_vccz .LBB0_535
